# adds dwordx4 row stores (v_permlane32_swap pairs) in the SB unit epilogue and the diff-attention finalize, gains read in one LDS batch
# speedup vs baseline: 1.0120x; 1.0028x over previous
.LBB0_246:
	v_readlane_b32 s0, v254, 30
	v_lshlrev_b64 v[66:67], 11, v[146:147]
	v_readlane_b32 s1, v254, 31
	s_mov_b32 s41, s85
	v_mov_b32_e32 v149, v1
	v_lshl_add_u64 v[66:67], v[66:67], 1, s[0:1]
	v_lshl_add_u64 v[66:67], v[66:67], 0, s[40:41]
	v_lshl_add_u64 v[66:67], v[66:67], 0, v[148:149]
	v_and_b32_e32 v76, 32, v208
	v_lshrrev_b32_e32 v76, 2, v76
	v_mov_b32_e32 v77, 0
	v_lshl_add_u64 v[66:67], v[66:67], 0, v[76:77]
	v_cvt_pk_bf16_f32 v68, v50, v51
	v_cvt_pk_bf16_f32 v69, v52, v53
	v_cvt_pk_bf16_f32 v70, v54, v55
	v_cvt_pk_bf16_f32 v71, v56, v57
	s_nop 1
	v_permlane32_swap_b32_e32 v68, v70
	v_permlane32_swap_b32_e32 v69, v71
	global_store_dwordx4 v[66:67], v[68:71], off
	v_cvt_pk_bf16_f32 v72, v58, v59
	v_cvt_pk_bf16_f32 v73, v60, v61
	v_cvt_pk_bf16_f32 v74, v62, v63
	v_cvt_pk_bf16_f32 v75, v64, v65
	s_nop 1
	v_permlane32_swap_b32_e32 v72, v74
	v_permlane32_swap_b32_e32 v73, v75
	global_store_dwordx4 v[66:67], v[72:75], off offset:32
	v_cvt_pk_bf16_f32 v68, v34, v35
	v_cvt_pk_bf16_f32 v69, v36, v37
	v_cvt_pk_bf16_f32 v70, v38, v39
	v_cvt_pk_bf16_f32 v71, v40, v41
	s_nop 1
	v_permlane32_swap_b32_e32 v68, v70
	v_permlane32_swap_b32_e32 v69, v71
	global_store_dwordx4 v[66:67], v[68:71], off offset:64
	v_cvt_pk_bf16_f32 v72, v42, v43
	v_cvt_pk_bf16_f32 v73, v44, v45
	v_cvt_pk_bf16_f32 v74, v46, v47
	v_cvt_pk_bf16_f32 v75, v48, v49
	s_nop 1
	v_permlane32_swap_b32_e32 v72, v74
	v_permlane32_swap_b32_e32 v73, v75
	global_store_dwordx4 v[66:67], v[72:75], off offset:96
	v_cvt_pk_bf16_f32 v68, v18, v19
	v_cvt_pk_bf16_f32 v69, v20, v21
	v_cvt_pk_bf16_f32 v70, v22, v23
	v_cvt_pk_bf16_f32 v71, v24, v25
	s_nop 1
	v_permlane32_swap_b32_e32 v68, v70
	v_permlane32_swap_b32_e32 v69, v71
	global_store_dwordx4 v[66:67], v[68:71], off offset:128
	v_cvt_pk_bf16_f32 v72, v26, v27
	v_cvt_pk_bf16_f32 v73, v28, v29
	v_cvt_pk_bf16_f32 v74, v30, v31
	v_cvt_pk_bf16_f32 v75, v32, v33
	s_nop 1
	v_permlane32_swap_b32_e32 v72, v74
	v_permlane32_swap_b32_e32 v73, v75
	global_store_dwordx4 v[66:67], v[72:75], off offset:160
	v_cvt_pk_bf16_f32 v68, v2, v3
	v_cvt_pk_bf16_f32 v69, v4, v5
	v_cvt_pk_bf16_f32 v70, v6, v7
	v_cvt_pk_bf16_f32 v71, v8, v9
	s_nop 1
	v_permlane32_swap_b32_e32 v68, v70
	v_permlane32_swap_b32_e32 v69, v71
	global_store_dwordx4 v[66:67], v[68:71], off offset:192
	v_cvt_pk_bf16_f32 v72, v10, v11
	v_cvt_pk_bf16_f32 v73, v12, v13
	v_cvt_pk_bf16_f32 v74, v14, v15
	v_cvt_pk_bf16_f32 v75, v16, v17
	s_nop 1
	v_permlane32_swap_b32_e32 v72, v74
	v_permlane32_swap_b32_e32 v73, v75
	global_store_dwordx4 v[66:67], v[72:75], off offset:224
	s_add_i32 s15, s15, s34
	s_add_i32 s14, s14, s34
	s_cmpk_lt_i32 s15, 0x2000
	s_cbranch_scc0 .LBB0_239

.LBB0_285:
	v_readlane_b32 s28, v254, 60
	s_andn2_b64 vcc, exec, s[0:1]
	v_readlane_b32 s29, v254, 61
	v_mov_b64_e32 v[198:199], v[194:195]
	s_waitcnt lgkmcnt(0)
	s_barrier
	s_cbranch_vccnz .LBB0_250
	v_readlane_b32 s0, v254, 50
	v_mov_b32_e32 v68, v50
	s_lshl_b32 s84, s50, 1
	v_mov_b32_e32 v0, s0
	s_lshl_b32 s0, s14, 14
	s_add_i32 s0, s0, 0
	v_lshl_add_u32 v70, v203, 2, s0
	ds_read2st64_b32 v[72:73], v70 offset1:1
	ds_read_b32 v69, v0
	s_mov_b32 s0, 0xf800000
	v_mov_b32_e32 v203, v1
	s_waitcnt lgkmcnt(1)
	v_mov_b32_e32 v67, v72
	s_waitcnt lgkmcnt(0)
	v_pk_mul_f32 v[74:75], v[68:69], v[66:67]
	v_mov_b32_e32 v67, v73
	ds_read2st64_b32 v[72:73], v70 offset0:2 offset1:3
	v_mov_b32_e32 v68, v51
	v_pk_mul_f32 v[50:51], v[68:69], v[66:67]
	v_mov_b32_e32 v68, v52
	v_sub_f32_e32 v0, v74, v75
	s_waitcnt lgkmcnt(0)
	v_mov_b32_e32 v67, v72
	v_pk_mul_f32 v[74:75], v[68:69], v[66:67]
	v_mov_b32_e32 v67, v73
	ds_read2st64_b32 v[72:73], v70 offset0:4 offset1:5
	v_mov_b32_e32 v68, v53
	v_pk_mul_f32 v[52:53], v[68:69], v[66:67]
	v_mov_b32_e32 v68, v54
	v_sub_f32_e32 v50, v50, v51
	s_waitcnt lgkmcnt(0)
	v_mov_b32_e32 v67, v72
	v_sub_f32_e32 v51, v74, v75
	v_pk_mul_f32 v[74:75], v[68:69], v[66:67]
	v_mov_b32_e32 v67, v73
	ds_read2st64_b32 v[72:73], v70 offset0:6 offset1:7
	v_mov_b32_e32 v68, v55
	v_pk_mul_f32 v[54:55], v[68:69], v[66:67]
	v_mov_b32_e32 v68, v56
	v_sub_f32_e32 v52, v52, v53
	s_waitcnt lgkmcnt(0)
	v_mov_b32_e32 v67, v72
	v_sub_f32_e32 v53, v74, v75
	v_pk_mul_f32 v[74:75], v[68:69], v[66:67]
	v_mov_b32_e32 v67, v73
	ds_read2st64_b32 v[72:73], v70 offset0:8 offset1:9
	v_mov_b32_e32 v68, v57
	v_pk_mul_f32 v[56:57], v[68:69], v[66:67]
	v_mov_b32_e32 v68, v58
	v_sub_f32_e32 v54, v54, v55
	s_waitcnt lgkmcnt(0)
	v_mov_b32_e32 v67, v72
	v_sub_f32_e32 v55, v74, v75
	v_pk_mul_f32 v[74:75], v[68:69], v[66:67]
	v_mov_b32_e32 v67, v73
	ds_read2st64_b32 v[72:73], v70 offset0:10 offset1:11
	v_mov_b32_e32 v68, v59
	v_pk_mul_f32 v[58:59], v[68:69], v[66:67]
	v_mov_b32_e32 v68, v60
	v_sub_f32_e32 v56, v56, v57
	s_waitcnt lgkmcnt(0)
	v_mov_b32_e32 v67, v72
	v_sub_f32_e32 v57, v74, v75
	v_pk_mul_f32 v[74:75], v[68:69], v[66:67]
	v_mov_b32_e32 v67, v73
	ds_read2st64_b32 v[72:73], v70 offset0:12 offset1:13
	v_mov_b32_e32 v68, v61
	v_pk_mul_f32 v[60:61], v[68:69], v[66:67]
	v_mov_b32_e32 v68, v62
	v_sub_f32_e32 v58, v58, v59
	s_waitcnt lgkmcnt(0)
	v_mov_b32_e32 v67, v72
	v_sub_f32_e32 v59, v74, v75
	v_pk_mul_f32 v[74:75], v[68:69], v[66:67]
	v_mov_b32_e32 v67, v73
	ds_read2st64_b32 v[72:73], v70 offset0:14 offset1:15
	v_mov_b32_e32 v68, v63
	v_pk_mul_f32 v[62:63], v[68:69], v[66:67]
	v_mov_b32_e32 v68, v64
	v_sub_f32_e32 v60, v60, v61
	s_waitcnt lgkmcnt(0)
	v_mov_b32_e32 v67, v72
	v_sub_f32_e32 v61, v74, v75
	v_pk_mul_f32 v[74:75], v[68:69], v[66:67]
	v_mov_b32_e32 v67, v73
	ds_read2st64_b32 v[72:73], v70 offset0:16 offset1:17
	v_mov_b32_e32 v68, v65
	v_pk_mul_f32 v[64:65], v[68:69], v[66:67]
	v_mov_b32_e32 v68, v34
	v_sub_f32_e32 v62, v62, v63
	s_waitcnt lgkmcnt(0)
	v_mov_b32_e32 v67, v72
	v_sub_f32_e32 v63, v74, v75
	v_pk_mul_f32 v[74:75], v[68:69], v[66:67]
	v_mov_b32_e32 v68, v35
	v_mov_b32_e32 v67, v73
	v_pk_mul_f32 v[72:73], v[68:69], v[66:67]
	v_mov_b32_e32 v68, v36
	v_sub_f32_e32 v35, v72, v73
	ds_read2st64_b32 v[72:73], v70 offset0:18 offset1:19
	v_sub_f32_e32 v34, v74, v75
	v_sub_f32_e32 v64, v64, v65
	s_waitcnt lgkmcnt(0)
	v_mov_b32_e32 v67, v72
	v_pk_mul_f32 v[74:75], v[68:69], v[66:67]
	v_mov_b32_e32 v68, v37
	v_mov_b32_e32 v67, v73
	v_pk_mul_f32 v[72:73], v[68:69], v[66:67]
	v_mov_b32_e32 v68, v38
	v_sub_f32_e32 v37, v72, v73
	ds_read2st64_b32 v[72:73], v70 offset0:20 offset1:21
	v_sub_f32_e32 v36, v74, v75
	s_waitcnt lgkmcnt(0)
	v_mov_b32_e32 v67, v72
	v_pk_mul_f32 v[74:75], v[68:69], v[66:67]
	v_mov_b32_e32 v68, v39
	v_mov_b32_e32 v67, v73
	v_pk_mul_f32 v[72:73], v[68:69], v[66:67]
	v_mov_b32_e32 v68, v40
	v_sub_f32_e32 v39, v72, v73
	ds_read2st64_b32 v[72:73], v70 offset0:22 offset1:23
	v_sub_f32_e32 v38, v74, v75
	s_waitcnt lgkmcnt(0)
	v_mov_b32_e32 v67, v72
	v_pk_mul_f32 v[74:75], v[68:69], v[66:67]
	v_mov_b32_e32 v68, v41
	v_mov_b32_e32 v67, v73
	v_pk_mul_f32 v[72:73], v[68:69], v[66:67]
	v_mov_b32_e32 v68, v42
	v_sub_f32_e32 v41, v72, v73
	ds_read2st64_b32 v[72:73], v70 offset0:24 offset1:25
	v_sub_f32_e32 v40, v74, v75
	s_waitcnt lgkmcnt(0)
	v_mov_b32_e32 v67, v72
	v_pk_mul_f32 v[74:75], v[68:69], v[66:67]
	v_mov_b32_e32 v68, v43
	v_mov_b32_e32 v67, v73
	v_pk_mul_f32 v[72:73], v[68:69], v[66:67]
	v_mov_b32_e32 v68, v44
	v_sub_f32_e32 v43, v72, v73
	ds_read2st64_b32 v[72:73], v70 offset0:26 offset1:27
	v_sub_f32_e32 v42, v74, v75
	s_waitcnt lgkmcnt(0)
	v_mov_b32_e32 v67, v72
	v_pk_mul_f32 v[74:75], v[68:69], v[66:67]
	v_mov_b32_e32 v68, v45
	v_mov_b32_e32 v67, v73
	v_pk_mul_f32 v[72:73], v[68:69], v[66:67]
	v_mov_b32_e32 v68, v46
	v_sub_f32_e32 v45, v72, v73
	ds_read2st64_b32 v[72:73], v70 offset0:28 offset1:29
	v_sub_f32_e32 v44, v74, v75
	s_waitcnt lgkmcnt(0)
	v_mov_b32_e32 v67, v72
	v_pk_mul_f32 v[74:75], v[68:69], v[66:67]
	v_mov_b32_e32 v68, v47
	v_mov_b32_e32 v67, v73
	v_pk_mul_f32 v[72:73], v[68:69], v[66:67]
	v_mov_b32_e32 v68, v48
	v_sub_f32_e32 v47, v72, v73
	ds_read2st64_b32 v[72:73], v70 offset0:30 offset1:31
	v_sub_f32_e32 v46, v74, v75
	s_waitcnt lgkmcnt(0)
	v_mov_b32_e32 v67, v72
	v_pk_mul_f32 v[74:75], v[68:69], v[66:67]
	v_mov_b32_e32 v68, v49
	v_mov_b32_e32 v67, v73
	v_pk_mul_f32 v[72:73], v[68:69], v[66:67]
	v_mov_b32_e32 v68, v18
	v_sub_f32_e32 v49, v72, v73
	ds_read2st64_b32 v[72:73], v70 offset0:32 offset1:33
	v_sub_f32_e32 v48, v74, v75
	s_waitcnt lgkmcnt(0)
	v_mov_b32_e32 v67, v72
	v_pk_mul_f32 v[74:75], v[68:69], v[66:67]
	v_mov_b32_e32 v68, v19
	v_mov_b32_e32 v67, v73
	v_pk_mul_f32 v[72:73], v[68:69], v[66:67]
	v_mov_b32_e32 v68, v20
	v_sub_f32_e32 v19, v72, v73
	ds_read2st64_b32 v[72:73], v70 offset0:34 offset1:35
	v_sub_f32_e32 v18, v74, v75
	s_waitcnt lgkmcnt(0)
	v_mov_b32_e32 v67, v72
	v_pk_mul_f32 v[74:75], v[68:69], v[66:67]
	v_mov_b32_e32 v68, v21
	v_mov_b32_e32 v67, v73
	v_pk_mul_f32 v[72:73], v[68:69], v[66:67]
	v_mov_b32_e32 v68, v22
	v_sub_f32_e32 v21, v72, v73
	ds_read2st64_b32 v[72:73], v70 offset0:36 offset1:37
	v_sub_f32_e32 v20, v74, v75
	s_waitcnt lgkmcnt(0)
	v_mov_b32_e32 v67, v72
	v_pk_mul_f32 v[74:75], v[68:69], v[66:67]
	v_mov_b32_e32 v68, v23
	v_mov_b32_e32 v67, v73
	v_pk_mul_f32 v[72:73], v[68:69], v[66:67]
	v_mov_b32_e32 v68, v24
	v_sub_f32_e32 v23, v72, v73
	ds_read2st64_b32 v[72:73], v70 offset0:38 offset1:39
	v_sub_f32_e32 v22, v74, v75
	s_waitcnt lgkmcnt(0)
	v_mov_b32_e32 v67, v72
	v_pk_mul_f32 v[74:75], v[68:69], v[66:67]
	v_mov_b32_e32 v68, v25
	v_mov_b32_e32 v67, v73
	v_pk_mul_f32 v[72:73], v[68:69], v[66:67]
	v_mov_b32_e32 v68, v26
	v_sub_f32_e32 v25, v72, v73
	ds_read2st64_b32 v[72:73], v70 offset0:40 offset1:41
	v_sub_f32_e32 v24, v74, v75
	s_waitcnt lgkmcnt(0)
	v_mov_b32_e32 v67, v72
	v_pk_mul_f32 v[74:75], v[68:69], v[66:67]
	v_mov_b32_e32 v68, v27
	v_mov_b32_e32 v67, v73
	v_pk_mul_f32 v[72:73], v[68:69], v[66:67]
	v_mov_b32_e32 v68, v28
	v_sub_f32_e32 v27, v72, v73
	ds_read2st64_b32 v[72:73], v70 offset0:42 offset1:43
	v_sub_f32_e32 v26, v74, v75
	s_waitcnt lgkmcnt(0)
	v_mov_b32_e32 v67, v72
	v_pk_mul_f32 v[74:75], v[68:69], v[66:67]
	v_mov_b32_e32 v68, v29
	v_mov_b32_e32 v67, v73
	v_pk_mul_f32 v[72:73], v[68:69], v[66:67]
	v_mov_b32_e32 v68, v30
	v_sub_f32_e32 v29, v72, v73
	ds_read2st64_b32 v[72:73], v70 offset0:44 offset1:45
	v_sub_f32_e32 v28, v74, v75
	s_waitcnt lgkmcnt(0)
	v_mov_b32_e32 v67, v72
	v_pk_mul_f32 v[74:75], v[68:69], v[66:67]
	v_mov_b32_e32 v68, v31
	v_mov_b32_e32 v67, v73
	v_pk_mul_f32 v[72:73], v[68:69], v[66:67]
	v_mov_b32_e32 v68, v32
	v_sub_f32_e32 v31, v72, v73
	ds_read2st64_b32 v[72:73], v70 offset0:46 offset1:47
	v_sub_f32_e32 v30, v74, v75
	s_waitcnt lgkmcnt(0)
	v_mov_b32_e32 v67, v72
	v_pk_mul_f32 v[74:75], v[68:69], v[66:67]
	v_mov_b32_e32 v68, v33
	v_mov_b32_e32 v67, v73
	v_pk_mul_f32 v[72:73], v[68:69], v[66:67]
	v_mov_b32_e32 v68, v2
	v_sub_f32_e32 v33, v72, v73
	ds_read2st64_b32 v[72:73], v70 offset0:48 offset1:49
	v_sub_f32_e32 v32, v74, v75
	s_waitcnt lgkmcnt(0)
	v_mov_b32_e32 v67, v72
	v_pk_mul_f32 v[74:75], v[68:69], v[66:67]
	v_mov_b32_e32 v68, v3
	v_mov_b32_e32 v67, v73
	v_pk_mul_f32 v[2:3], v[68:69], v[66:67]
	v_mov_b32_e32 v68, v4
	v_sub_f32_e32 v71, v2, v3
	ds_read2st64_b32 v[2:3], v70 offset0:50 offset1:51
	v_sub_f32_e32 v65, v74, v75
	s_waitcnt lgkmcnt(0)
	v_mov_b32_e32 v67, v2
	v_pk_mul_f32 v[72:73], v[68:69], v[66:67]
	v_mov_b32_e32 v68, v5
	v_mov_b32_e32 v67, v3
	v_pk_mul_f32 v[2:3], v[68:69], v[66:67]
	v_sub_f32_e32 v72, v72, v73
	v_sub_f32_e32 v73, v2, v3
	ds_read2st64_b32 v[2:3], v70 offset0:52 offset1:53
	v_mov_b32_e32 v68, v6
	s_waitcnt lgkmcnt(0)
	v_mov_b32_e32 v67, v2
	v_pk_mul_f32 v[4:5], v[68:69], v[66:67]
	v_mov_b32_e32 v68, v7
	v_mov_b32_e32 v67, v3
	v_pk_mul_f32 v[2:3], v[68:69], v[66:67]
	v_mov_b32_e32 v68, v8
	v_sub_f32_e32 v75, v2, v3
	ds_read2st64_b32 v[2:3], v70 offset0:54 offset1:55
	v_sub_f32_e32 v74, v4, v5
	s_waitcnt lgkmcnt(0)
	v_mov_b32_e32 v67, v2
	v_pk_mul_f32 v[4:5], v[68:69], v[66:67]
	v_mov_b32_e32 v68, v9
	v_mov_b32_e32 v67, v3
	v_pk_mul_f32 v[2:3], v[68:69], v[66:67]
	v_mov_b32_e32 v68, v10
	v_sub_f32_e32 v9, v2, v3
	ds_read2st64_b32 v[2:3], v70 offset0:56 offset1:57
	v_sub_f32_e32 v8, v4, v5
	s_waitcnt lgkmcnt(0)
	v_mov_b32_e32 v67, v2
	v_pk_mul_f32 v[4:5], v[68:69], v[66:67]
	v_mov_b32_e32 v68, v11
	v_mov_b32_e32 v67, v3
	v_pk_mul_f32 v[2:3], v[68:69], v[66:67]
	v_mov_b32_e32 v68, v12
	v_sub_f32_e32 v11, v2, v3
	ds_read2st64_b32 v[2:3], v70 offset0:58 offset1:59
	v_sub_f32_e32 v10, v4, v5
	s_waitcnt lgkmcnt(0)
	v_mov_b32_e32 v67, v2
	v_pk_mul_f32 v[4:5], v[68:69], v[66:67]
	v_mov_b32_e32 v68, v13
	v_mov_b32_e32 v67, v3
	v_pk_mul_f32 v[2:3], v[68:69], v[66:67]
	v_sub_f32_e32 v12, v4, v5
	v_sub_f32_e32 v13, v2, v3
	ds_read2st64_b32 v[2:3], v70 offset0:60 offset1:61
	v_mov_b32_e32 v4, v69
	s_waitcnt lgkmcnt(0)
	v_pk_mul_f32 v[2:3], v[4:5], v[2:3] op_sel_hi:[0,1]
	v_pk_fma_f32 v[2:3], v[14:15], v[66:67], v[2:3] op_sel_hi:[1,0,1] neg_lo:[0,0,1] neg_hi:[0,0,1]
	ds_read2st64_b32 v[14:15], v70 offset0:62 offset1:63
	v_pk_mul_f32 v[6:7], v[2:3], v[2:3]
	s_waitcnt lgkmcnt(0)
	v_pk_mul_f32 v[4:5], v[4:5], v[14:15] op_sel_hi:[0,1]
	v_pk_fma_f32 v[4:5], v[16:17], v[66:67], v[4:5] op_sel_hi:[1,0,1] neg_lo:[0,0,1] neg_hi:[0,0,1]
	v_mul_f32_e32 v16, v0, v0
	v_fmac_f32_e32 v16, v50, v50
	v_fmac_f32_e32 v16, v51, v51
	v_fmac_f32_e32 v16, v52, v52
	v_fmac_f32_e32 v16, v53, v53
	v_fmac_f32_e32 v16, v54, v54
	v_fmac_f32_e32 v16, v55, v55
	v_fmac_f32_e32 v16, v56, v56
	v_fmac_f32_e32 v16, v57, v57
	v_fmac_f32_e32 v16, v58, v58
	v_fmac_f32_e32 v16, v59, v59
	v_fmac_f32_e32 v16, v60, v60
	v_fmac_f32_e32 v16, v61, v61
	v_fmac_f32_e32 v16, v62, v62
	v_fmac_f32_e32 v16, v63, v63
	v_fmac_f32_e32 v16, v64, v64
	v_fmac_f32_e32 v16, v34, v34
	v_fmac_f32_e32 v16, v35, v35
	v_fmac_f32_e32 v16, v36, v36
	v_fmac_f32_e32 v16, v37, v37
	v_fmac_f32_e32 v16, v38, v38
	v_fmac_f32_e32 v16, v39, v39
	v_fmac_f32_e32 v16, v40, v40
	v_fmac_f32_e32 v16, v41, v41
	v_fmac_f32_e32 v16, v42, v42
	v_fmac_f32_e32 v16, v43, v43
	v_fmac_f32_e32 v16, v44, v44
	v_fmac_f32_e32 v16, v45, v45
	v_fmac_f32_e32 v16, v46, v46
	v_fmac_f32_e32 v16, v47, v47
	v_fmac_f32_e32 v16, v48, v48
	v_fmac_f32_e32 v16, v49, v49
	v_fmac_f32_e32 v16, v18, v18
	v_fmac_f32_e32 v16, v19, v19
	v_fmac_f32_e32 v16, v20, v20
	v_fmac_f32_e32 v16, v21, v21
	v_fmac_f32_e32 v16, v22, v22
	v_fmac_f32_e32 v16, v23, v23
	v_fmac_f32_e32 v16, v24, v24
	v_fmac_f32_e32 v16, v25, v25
	v_fmac_f32_e32 v16, v26, v26
	v_fmac_f32_e32 v16, v27, v27
	v_fmac_f32_e32 v16, v28, v28
	v_fmac_f32_e32 v16, v29, v29
	v_fmac_f32_e32 v16, v30, v30
	v_fmac_f32_e32 v16, v31, v31
	v_fmac_f32_e32 v16, v32, v32
	v_fmac_f32_e32 v16, v33, v33
	v_fmac_f32_e32 v16, v65, v65
	v_fmac_f32_e32 v16, v71, v71
	v_fmac_f32_e32 v16, v72, v72
	v_fmac_f32_e32 v16, v73, v73
	v_fmac_f32_e32 v16, v74, v74
	v_fmac_f32_e32 v16, v75, v75
	v_fmac_f32_e32 v16, v8, v8
	v_fmac_f32_e32 v16, v9, v9
	v_fmac_f32_e32 v16, v10, v10
	v_fmac_f32_e32 v16, v11, v11
	v_fmac_f32_e32 v16, v12, v12
	v_fmac_f32_e32 v16, v13, v13
	v_add_f32_e32 v6, v16, v6
	v_pk_mul_f32 v[14:15], v[4:5], v[4:5]
	v_add_f32_e32 v6, v6, v7
	v_add_f32_e32 v6, v6, v14
	v_add_f32_e32 v6, v6, v15
	v_mov_b32_e32 v7, v6
	v_mov_b32_e32 v14, v6
	s_nop 1
	v_permlane32_swap_b32_e32 v7, v14
	v_cndmask_b32_e64 v7, v7, v14, s[38:39]
	v_add_f32_e32 v6, v6, v7
	v_mov_b32_e32 v7, 0x3727c5ac
	v_fmamk_f32 v6, v6, 0x3c000000, v7
	v_cmp_gt_f32_e32 vcc, s0, v6
	v_mul_f32_e32 v7, 0x4f800000, v6
	s_nop 0
	v_cndmask_b32_e32 v6, v6, v7, vcc
	v_sqrt_f32_e32 v7, v6
	s_nop 0
	v_add_u32_e32 v14, -1, v7
	v_fma_f32 v15, -v14, v7, v6
	v_cmp_ge_f32_e64 s[0:1], 0, v15
	v_add_u32_e32 v15, 1, v7
	s_nop 0
	v_cndmask_b32_e64 v14, v7, v14, s[0:1]
	v_fma_f32 v7, -v15, v7, v6
	v_cmp_lt_f32_e64 s[0:1], 0, v7
	s_nop 1
	v_cndmask_b32_e64 v7, v14, v15, s[0:1]
	v_mul_f32_e32 v14, 0x37800000, v7
	v_cndmask_b32_e32 v7, v7, v14, vcc
	v_mov_b32_e32 v14, 0x260
	v_cmp_class_f32_e32 vcc, v6, v14
	s_nop 1
	v_cndmask_b32_e32 v6, v7, v6, vcc
	v_div_scale_f32 v7, s[0:1], v6, v6, 1.0
	v_rcp_f32_e32 v14, v7
	v_readlane_b32 s0, v254, 30
	v_readlane_b32 s1, v254, 31
	v_fma_f32 v15, -v7, v14, 1.0
	v_fmac_f32_e32 v14, v15, v14
	v_div_scale_f32 v15, vcc, 1.0, v6, 1.0
	v_mul_f32_e32 v16, v15, v14
	v_fma_f32 v17, -v7, v16, v15
	v_fmac_f32_e32 v16, v17, v14
	v_fma_f32 v7, -v7, v16, v15
	v_div_fmas_f32 v7, v7, v14, v16
	v_lshl_add_u32 v14, v214, 4, 0
	v_add_u32_e32 v67, 0x20400, v14
	v_div_fixup_f32 v66, v7, v6, 1.0
	v_lshl_add_u64 v[6:7], v[200:201], 1, s[0:1]
	v_lshl_add_u64 v[6:7], v[6:7], 0, s[84:85]
	v_lshl_add_u64 v[6:7], v[6:7], 0, v[202:203]
	v_lshl_add_u64 v[6:7], v[6:7], 0, v[202:203]
	ds_read_b128 v[82:85], v67
	ds_read_b128 v[86:89], v67 offset:32
	ds_read_b128 v[90:93], v67 offset:64
	ds_read_b128 v[94:97], v67 offset:96
	ds_read_b128 v[98:101], v67 offset:128
	ds_read_b128 v[102:105], v67 offset:160
	ds_read_b128 v[106:109], v67 offset:192
	ds_read_b128 v[110:113], v67 offset:224
	ds_read_b128 v[114:117], v67 offset:256
	ds_read_b128 v[118:121], v67 offset:288
	ds_read_b128 v[122:125], v67 offset:320
	ds_read_b128 v[126:129], v67 offset:352
	ds_read_b128 v[130:133], v67 offset:384
	ds_read_b128 v[134:137], v67 offset:416
	ds_read_b128 v[138:141], v67 offset:448
	ds_read_b128 v[142:145], v67 offset:480
	s_waitcnt lgkmcnt(0)
	v_mul_f32_e32 v154, v0, v66
	v_mul_f32_e32 v154, v154, v82
	v_mul_f32_e32 v155, v50, v66
	v_mul_f32_e32 v155, v155, v83
	v_mul_f32_e32 v156, v51, v66
	v_mul_f32_e32 v156, v156, v84
	v_mul_f32_e32 v157, v52, v66
	v_mul_f32_e32 v157, v157, v85
	v_mul_f32_e32 v158, v53, v66
	v_mul_f32_e32 v158, v158, v86
	v_mul_f32_e32 v159, v54, v66
	v_mul_f32_e32 v159, v159, v87
	v_mul_f32_e32 v160, v55, v66
	v_mul_f32_e32 v160, v160, v88
	v_mul_f32_e32 v161, v56, v66
	v_mul_f32_e32 v161, v161, v89
	v_cvt_pk_bf16_f32 v146, v154, v155
	v_cvt_pk_bf16_f32 v147, v156, v157
	v_cvt_pk_bf16_f32 v148, v158, v159
	v_cvt_pk_bf16_f32 v149, v160, v161
	s_nop 1
	v_permlane32_swap_b32_e32 v146, v148
	v_permlane32_swap_b32_e32 v147, v149
	global_store_dwordx4 v[6:7], v[146:149], off
	v_mul_f32_e32 v154, v57, v66
	v_mul_f32_e32 v154, v154, v90
	v_mul_f32_e32 v155, v58, v66
	v_mul_f32_e32 v155, v155, v91
	v_mul_f32_e32 v156, v59, v66
	v_mul_f32_e32 v156, v156, v92
	v_mul_f32_e32 v157, v60, v66
	v_mul_f32_e32 v157, v157, v93
	v_mul_f32_e32 v158, v61, v66
	v_mul_f32_e32 v158, v158, v94
	v_mul_f32_e32 v159, v62, v66
	v_mul_f32_e32 v159, v159, v95
	v_mul_f32_e32 v160, v63, v66
	v_mul_f32_e32 v160, v160, v96
	v_mul_f32_e32 v161, v64, v66
	v_mul_f32_e32 v161, v161, v97
	v_cvt_pk_bf16_f32 v150, v154, v155
	v_cvt_pk_bf16_f32 v151, v156, v157
	v_cvt_pk_bf16_f32 v152, v158, v159
	v_cvt_pk_bf16_f32 v153, v160, v161
	s_nop 1
	v_permlane32_swap_b32_e32 v150, v152
	v_permlane32_swap_b32_e32 v151, v153
	global_store_dwordx4 v[6:7], v[150:153], off offset:32
	v_mul_f32_e32 v154, v34, v66
	v_mul_f32_e32 v154, v154, v98
	v_mul_f32_e32 v155, v35, v66
	v_mul_f32_e32 v155, v155, v99
	v_mul_f32_e32 v156, v36, v66
	v_mul_f32_e32 v156, v156, v100
	v_mul_f32_e32 v157, v37, v66
	v_mul_f32_e32 v157, v157, v101
	v_mul_f32_e32 v158, v38, v66
	v_mul_f32_e32 v158, v158, v102
	v_mul_f32_e32 v159, v39, v66
	v_mul_f32_e32 v159, v159, v103
	v_mul_f32_e32 v160, v40, v66
	v_mul_f32_e32 v160, v160, v104
	v_mul_f32_e32 v161, v41, v66
	v_mul_f32_e32 v161, v161, v105
	v_cvt_pk_bf16_f32 v146, v154, v155
	v_cvt_pk_bf16_f32 v147, v156, v157
	v_cvt_pk_bf16_f32 v148, v158, v159
	v_cvt_pk_bf16_f32 v149, v160, v161
	s_nop 1
	v_permlane32_swap_b32_e32 v146, v148
	v_permlane32_swap_b32_e32 v147, v149
	global_store_dwordx4 v[6:7], v[146:149], off offset:64
	v_mul_f32_e32 v154, v42, v66
	v_mul_f32_e32 v154, v154, v106
	v_mul_f32_e32 v155, v43, v66
	v_mul_f32_e32 v155, v155, v107
	v_mul_f32_e32 v156, v44, v66
	v_mul_f32_e32 v156, v156, v108
	v_mul_f32_e32 v157, v45, v66
	v_mul_f32_e32 v157, v157, v109
	v_mul_f32_e32 v158, v46, v66
	v_mul_f32_e32 v158, v158, v110
	v_mul_f32_e32 v159, v47, v66
	v_mul_f32_e32 v159, v159, v111
	v_mul_f32_e32 v160, v48, v66
	v_mul_f32_e32 v160, v160, v112
	v_mul_f32_e32 v161, v49, v66
	v_mul_f32_e32 v161, v161, v113
	v_cvt_pk_bf16_f32 v150, v154, v155
	v_cvt_pk_bf16_f32 v151, v156, v157
	v_cvt_pk_bf16_f32 v152, v158, v159
	v_cvt_pk_bf16_f32 v153, v160, v161
	s_nop 1
	v_permlane32_swap_b32_e32 v150, v152
	v_permlane32_swap_b32_e32 v151, v153
	global_store_dwordx4 v[6:7], v[150:153], off offset:96
	v_mul_f32_e32 v154, v18, v66
	v_mul_f32_e32 v154, v154, v114
	v_mul_f32_e32 v155, v19, v66
	v_mul_f32_e32 v155, v155, v115
	v_mul_f32_e32 v156, v20, v66
	v_mul_f32_e32 v156, v156, v116
	v_mul_f32_e32 v157, v21, v66
	v_mul_f32_e32 v157, v157, v117
	v_mul_f32_e32 v158, v22, v66
	v_mul_f32_e32 v158, v158, v118
	v_mul_f32_e32 v159, v23, v66
	v_mul_f32_e32 v159, v159, v119
	v_mul_f32_e32 v160, v24, v66
	v_mul_f32_e32 v160, v160, v120
	v_mul_f32_e32 v161, v25, v66
	v_mul_f32_e32 v161, v161, v121
	v_cvt_pk_bf16_f32 v146, v154, v155
	v_cvt_pk_bf16_f32 v147, v156, v157
	v_cvt_pk_bf16_f32 v148, v158, v159
	v_cvt_pk_bf16_f32 v149, v160, v161
	s_nop 1
	v_permlane32_swap_b32_e32 v146, v148
	v_permlane32_swap_b32_e32 v147, v149
	global_store_dwordx4 v[6:7], v[146:149], off offset:128
	v_mul_f32_e32 v154, v26, v66
	v_mul_f32_e32 v154, v154, v122
	v_mul_f32_e32 v155, v27, v66
	v_mul_f32_e32 v155, v155, v123
	v_mul_f32_e32 v156, v28, v66
	v_mul_f32_e32 v156, v156, v124
	v_mul_f32_e32 v157, v29, v66
	v_mul_f32_e32 v157, v157, v125
	v_mul_f32_e32 v158, v30, v66
	v_mul_f32_e32 v158, v158, v126
	v_mul_f32_e32 v159, v31, v66
	v_mul_f32_e32 v159, v159, v127
	v_mul_f32_e32 v160, v32, v66
	v_mul_f32_e32 v160, v160, v128
	v_mul_f32_e32 v161, v33, v66
	v_mul_f32_e32 v161, v161, v129
	v_cvt_pk_bf16_f32 v150, v154, v155
	v_cvt_pk_bf16_f32 v151, v156, v157
	v_cvt_pk_bf16_f32 v152, v158, v159
	v_cvt_pk_bf16_f32 v153, v160, v161
	s_nop 1
	v_permlane32_swap_b32_e32 v150, v152
	v_permlane32_swap_b32_e32 v151, v153
	global_store_dwordx4 v[6:7], v[150:153], off offset:160
	v_mul_f32_e32 v154, v65, v66
	v_mul_f32_e32 v154, v154, v130
	v_mul_f32_e32 v155, v71, v66
	v_mul_f32_e32 v155, v155, v131
	v_mul_f32_e32 v156, v72, v66
	v_mul_f32_e32 v156, v156, v132
	v_mul_f32_e32 v157, v73, v66
	v_mul_f32_e32 v157, v157, v133
	v_mul_f32_e32 v158, v74, v66
	v_mul_f32_e32 v158, v158, v134
	v_mul_f32_e32 v159, v75, v66
	v_mul_f32_e32 v159, v159, v135
	v_mul_f32_e32 v160, v8, v66
	v_mul_f32_e32 v160, v160, v136
	v_mul_f32_e32 v161, v9, v66
	v_mul_f32_e32 v161, v161, v137
	v_cvt_pk_bf16_f32 v146, v154, v155
	v_cvt_pk_bf16_f32 v147, v156, v157
	v_cvt_pk_bf16_f32 v148, v158, v159
	v_cvt_pk_bf16_f32 v149, v160, v161
	s_nop 1
	v_permlane32_swap_b32_e32 v146, v148
	v_permlane32_swap_b32_e32 v147, v149
	global_store_dwordx4 v[6:7], v[146:149], off offset:192
	v_mul_f32_e32 v154, v10, v66
	v_mul_f32_e32 v154, v154, v138
	v_mul_f32_e32 v155, v11, v66
	v_mul_f32_e32 v155, v155, v139
	v_mul_f32_e32 v156, v12, v66
	v_mul_f32_e32 v156, v156, v140
	v_mul_f32_e32 v157, v13, v66
	v_mul_f32_e32 v157, v157, v141
	v_mul_f32_e32 v158, v2, v66
	v_mul_f32_e32 v158, v158, v142
	v_mul_f32_e32 v159, v3, v66
	v_mul_f32_e32 v159, v159, v143
	v_mul_f32_e32 v160, v4, v66
	v_mul_f32_e32 v160, v160, v144
	v_mul_f32_e32 v161, v5, v66
	v_mul_f32_e32 v161, v161, v145
	v_cvt_pk_bf16_f32 v150, v154, v155
	v_cvt_pk_bf16_f32 v151, v156, v157
	v_cvt_pk_bf16_f32 v152, v158, v159
	v_cvt_pk_bf16_f32 v153, v160, v161
	s_nop 1
	v_permlane32_swap_b32_e32 v150, v152
	v_permlane32_swap_b32_e32 v151, v153
	global_store_dwordx4 v[6:7], v[150:153], off offset:224
	s_branch .LBB0_250
